# flipped static priority: leading wave half at s_setprio 1 over each tile's K loop, trailing half at 0 (toggles removed; on top of v40)
# baseline (speedup 1.0000x reference)
;     __device__ bool next(int i, pg8::Unit& u) const { if (!base.next(i >> 1, u)) return false; u.seg = i & 1; return true; }
; template <class Epi, class Sched, bool ALIGN_EPI = false, bool SP2 = false>
; __device__ __forceinline__ void gemm_phase(PG8_LAS unsigned char* lds, const Gemm g, const Sched& S, const Epi& E) {
;     ...
;         const bool has_next = S.next(ui + 1, nxt);
;         const char* nA = has_next ? (const char*)(nxt.seg ? g.A2 : g.A) + (size_t)nxt.pm * tstep : cA; const char* nB = has_next ? (const char*)(nxt.seg ? g.Bt2 : g.Bt) + (size_t)nxt.pn * tstep : cB;
.LBB0_130:
	s_ashr_i32 s41, s40, 31
	s_lshl_b64 s[42:43], s[40:41], 20
	s_add_u32 s42, s35, s42
	s_addc_u32 s43, s54, s43
	s_and_b64 s[44:45], s[6:7], exec
	s_cselect_b32 s33, s43, s49
	s_cselect_b32 s41, s42, s48
	s_ashr_i32 s39, s38, 31
	s_lshl_b64 s[44:45], s[38:39], 20
	s_add_u32 s44, s55, s44
	s_addc_u32 s45, s56, s45
	s_and_b64 s[52:53], s[6:7], exec
	s_cselect_b32 s39, s45, s51
	s_cselect_b32 s47, s44, s50
	s_add_u32 s48, s48, 0x80080
	s_addc_u32 s49, s49, 0
	s_add_u32 s71, s50, 0x100
	v_mov_b32_e32 v28, 0
	s_addc_u32 s72, s51, 0
	s_mov_b32 s73, -2
	s_cmp_lg_u64 s[14:15], 0
	s_cbranch_scc0 .Lsp0_lead
	s_setprio 1

;     __device__ bool next(int i, pg8::Unit& u) const { if (!base.next(i >> 1, u)) return false; u.seg = i & 1; return true; }
; template <class Epi, class Sched, bool ALIGN_EPI = false, bool SP2 = false>
; __device__ __forceinline__ void gemm_phase(PG8_LAS unsigned char* lds, const Gemm g, const Sched& S, const Epi& E) {
;     ...
;         const bool has_next = S.next(ui + 1, nxt);
;         const char* nA = has_next ? (const char*)(nxt.seg ? g.A2 : g.A) + (size_t)nxt.pm * tstep : cA; const char* nB = has_next ? (const char*)(nxt.seg ? g.Bt2 : g.Bt) + (size_t)nxt.pn * tstep : cB;
.LBB0_749:
	s_ashr_i32 s25, s24, 31
	s_lshl_b64 s[26:27], s[24:25], 20
	s_add_u32 s26, s35, s26
	s_addc_u32 s27, s44, s27
	s_and_b64 s[28:29], s[0:1], exec
	s_cselect_b32 s25, s27, s39
	s_cselect_b32 s62, s26, s38
	s_ashr_i32 s23, s22, 31
	s_lshl_b64 s[28:29], s[22:23], 20
	s_add_u32 s28, s45, s28
	s_addc_u32 s29, s46, s29
	s_and_b64 s[36:37], s[0:1], exec
	s_cselect_b32 s23, s29, s41
	s_cselect_b32 s63, s28, s40
	s_add_u32 s38, s38, 0x80080
	s_addc_u32 s39, s39, 0
	s_add_u32 s64, s40, 0x100
	v_mov_b32_e32 v0, 0
	s_addc_u32 s65, s41, 0
	s_mov_b32 s66, -2
	s_cmp_lg_u64 s[12:13], 0
	s_cbranch_scc0 .Lsp1_lead
	s_setprio 1

;     __device__ bool next(int i, pg8::Unit& u) const { if (!base.next(i >> 1, u)) return false; u.seg = i & 1; return true; }
; template <class Epi, class Sched, bool ALIGN_EPI = false, bool SP2 = false>
; __device__ __forceinline__ void gemm_phase(PG8_LAS unsigned char* lds, const Gemm g, const Sched& S, const Epi& E) {
;     ...
;         const bool has_next = S.next(ui + 1, nxt);
;         const char* nA = has_next ? (const char*)(nxt.seg ? g.A2 : g.A) + (size_t)nxt.pm * tstep : cA; const char* nB = has_next ? (const char*)(nxt.seg ? g.Bt2 : g.Bt) + (size_t)nxt.pn * tstep : cB;
.LBB0_881:
	s_ashr_i32 s49, s48, 31
	s_lshl_b64 s[36:37], s[48:49], 20
	s_add_u32 s50, s33, s36
	s_addc_u32 s51, s35, s37
	s_and_b64 s[36:37], s[12:13], exec
	s_cselect_b32 s15, s51, s19
	s_cselect_b32 s17, s50, s18
	s_ashr_i32 s47, s46, 31
	s_lshl_b64 s[36:37], s[46:47], 20
	s_add_u32 s52, s56, s36
	s_addc_u32 s53, s57, s37
	s_and_b64 s[36:37], s[12:13], exec
	s_cselect_b32 s47, s53, s21
	s_cselect_b32 s49, s52, s20
	s_add_u32 s18, s18, 0x80080
	s_addc_u32 s19, s19, 0
	s_add_u32 s76, s20, 0x100
	v_mov_b32_e32 v120, 0
	s_addc_u32 s77, s21, 0
	s_mov_b32 s78, -2
	s_cmp_lg_u64 s[30:31], 0
	s_cbranch_scc0 .Lsp2_lead
	s_setprio 1

; template <class Epi, class Sched, bool ALIGN_EPI = false, bool SP2 = false>
; __device__ __forceinline__ void gemm_phase(PG8_LAS unsigned char* lds, const Gemm g, const Sched& S, const Epi& E) {
;     ...
;         const char* nA = has_next ? (const char*)(nxt.seg ? g.A2 : g.A) + (size_t)nxt.pm * tstep : cA; const char* nB = has_next ? (const char*)(nxt.seg ? g.Bt2 : g.Bt) + (size_t)nxt.pn * tstep : cB;
;         for (int t = 0; t < nt; t += 2) {
;             const bool last = (t == nt - 2);
.LBB0_1059:
	s_add_u32 s24, s24, 0x158080
	s_addc_u32 s25, s25, 0
	s_add_u32 s58, s26, 0x100
	v_mov_b32_e32 v0, 0
	s_addc_u32 s59, s27, 0
	s_mov_b32 s60, -2
	s_cmp_lg_u64 s[12:13], 0
	s_cbranch_scc0 .Lsp3_lead
	s_setprio 1
